# all sub-noise levers stacked on the best version: xattn dwordx4 stores + gMLP dwordx4 RMW + packed FFN-in blocks + dropped redundant FFN-in wait
# baseline (speedup 1.0000x reference)
.LBB0_673:
	v_add3_u32 v132, v136, v137, s52
	ds_read_b128 v[128:131], v132
	ds_read_b128 v[138:141], v132 offset:2048
	ds_read_b128 v[154:157], v132 offset:4096
	ds_read_b128 v[158:161], v132 offset:6144
	v_add3_u32 v132, v134, v137, s81
	ds_read_b128 v[162:165], v132
	ds_read_b128 v[166:169], v132 offset:2048
	ds_read_b128 v[170:173], v132 offset:4096
	ds_read_b128 v[174:177], v132 offset:6144
	ds_read_b128 v[178:181], v132 offset:8192
	ds_read_b128 v[182:185], v132 offset:10240
	ds_read_b128 v[186:189], v132 offset:12288
	ds_read_b128 v[216:219], v132 offset:14336
	s_waitcnt lgkmcnt(0)
	v_mfma_f32_16x16x32_bf16 v[116:119], v[128:131], v[162:165], v[116:119]
	v_mfma_f32_16x16x32_bf16 v[108:111], v[138:141], v[162:165], v[108:111]
	v_mfma_f32_16x16x32_bf16 v[100:103], v[154:157], v[162:165], v[100:103]
	v_mfma_f32_16x16x32_bf16 v[88:91], v[158:161], v[162:165], v[88:91]
	v_mfma_f32_16x16x32_bf16 v[76:79], v[128:131], v[166:169], v[76:79]
	v_mfma_f32_16x16x32_bf16 v[68:71], v[138:141], v[166:169], v[68:71]
	v_mfma_f32_16x16x32_bf16 v[56:59], v[154:157], v[166:169], v[56:59]
	v_mfma_f32_16x16x32_bf16 v[44:47], v[158:161], v[166:169], v[44:47]
	v_mfma_f32_16x16x32_bf16 v[36:39], v[128:131], v[170:173], v[36:39]
	v_mfma_f32_16x16x32_bf16 v[32:35], v[138:141], v[170:173], v[32:35]
	v_mfma_f32_16x16x32_bf16 v[28:31], v[154:157], v[170:173], v[28:31]
	v_mfma_f32_16x16x32_bf16 v[24:27], v[158:161], v[170:173], v[24:27]
	v_mfma_f32_16x16x32_bf16 v[20:23], v[128:131], v[174:177], v[20:23]
	v_mfma_f32_16x16x32_bf16 v[16:19], v[138:141], v[174:177], v[16:19]
	v_mfma_f32_16x16x32_bf16 v[12:15], v[154:157], v[174:177], v[12:15]
	v_mfma_f32_16x16x32_bf16 v[8:11], v[158:161], v[174:177], v[8:11]
	v_add3_u32 v132, v136, v135, s52
	v_add3_u32 v144, v134, v135, s81
	ds_read_b128 v[162:165], v132
	ds_read_b128 v[166:169], v132 offset:2048
	ds_read_b128 v[170:173], v132 offset:4096
	ds_read_b128 v[174:177], v132 offset:6144
	ds_read_b128 v[132:135], v144
	ds_read_b128 v[220:223], v144 offset:2048
	ds_read_b128 v[224:227], v144 offset:4096
	ds_read_b128 v[228:231], v144 offset:6144
	v_mfma_f32_16x16x32_bf16 v[4:7], v[128:131], v[178:181], v[4:7]
	v_mfma_f32_16x16x32_bf16 v[0:3], v[138:141], v[178:181], v[0:3]
	v_mfma_f32_16x16x32_bf16 v[40:43], v[154:157], v[178:181], v[40:43]
	v_mfma_f32_16x16x32_bf16 v[48:51], v[158:161], v[178:181], v[48:51]
	v_mfma_f32_16x16x32_bf16 v[178:181], v[128:131], v[182:185], v[52:55]
	v_mfma_f32_16x16x32_bf16 v[232:235], v[138:141], v[182:185], v[60:63]
	v_mfma_f32_16x16x32_bf16 v[236:239], v[154:157], v[182:185], v[64:67]
	v_mfma_f32_16x16x32_bf16 v[182:185], v[158:161], v[182:185], v[72:75]
	v_mfma_f32_16x16x32_bf16 v[240:243], v[128:131], v[186:189], v[80:83]
	v_mfma_f32_16x16x32_bf16 v[244:247], v[138:141], v[186:189], v[84:87]
	v_mfma_f32_16x16x32_bf16 v[248:251], v[154:157], v[186:189], v[92:95]
	v_mfma_f32_16x16x32_bf16 v[186:189], v[158:161], v[186:189], v[96:99]
	v_mfma_f32_16x16x32_bf16 v[128:131], v[128:131], v[216:219], v[104:107]
	v_mfma_f32_16x16x32_bf16 v[136:139], v[138:141], v[216:219], v[112:115]
	v_mfma_f32_16x16x32_bf16 v[140:143], v[154:157], v[216:219], v[120:123]
	v_mfma_f32_16x16x32_bf16 v[154:157], v[158:161], v[216:219], v[124:127]
	ds_read_b128 v[158:161], v144 offset:8192
	ds_read_b128 v[216:219], v144 offset:10240
	ds_read_b128 v[146:149], v144 offset:12288
	ds_read_b128 v[206:209], v144 offset:14336
	s_waitcnt lgkmcnt(0)
	v_mfma_f32_16x16x32_bf16 v[124:127], v[162:165], v[132:135], v[116:119]
	v_mfma_f32_16x16x32_bf16 v[120:123], v[166:169], v[132:135], v[108:111]
	v_mfma_f32_16x16x32_bf16 v[116:119], v[170:173], v[132:135], v[100:103]
	v_mfma_f32_16x16x32_bf16 v[112:115], v[174:177], v[132:135], v[88:91]
	v_mfma_f32_16x16x32_bf16 v[108:111], v[162:165], v[220:223], v[76:79]
	v_mfma_f32_16x16x32_bf16 v[104:107], v[166:169], v[220:223], v[68:71]
	v_mfma_f32_16x16x32_bf16 v[100:103], v[170:173], v[220:223], v[56:59]
	v_mfma_f32_16x16x32_bf16 v[96:99], v[174:177], v[220:223], v[44:47]
	v_mfma_f32_16x16x32_bf16 v[92:95], v[162:165], v[224:227], v[36:39]
	v_mfma_f32_16x16x32_bf16 v[88:91], v[166:169], v[224:227], v[32:35]
	v_mfma_f32_16x16x32_bf16 v[84:87], v[170:173], v[224:227], v[28:31]
	v_mfma_f32_16x16x32_bf16 v[80:83], v[174:177], v[224:227], v[24:27]
	v_mfma_f32_16x16x32_bf16 v[76:79], v[162:165], v[228:231], v[20:23]
	v_mfma_f32_16x16x32_bf16 v[72:75], v[166:169], v[228:231], v[16:19]
	v_mfma_f32_16x16x32_bf16 v[68:71], v[170:173], v[228:231], v[12:15]
	v_mfma_f32_16x16x32_bf16 v[64:67], v[174:177], v[228:231], v[8:11]
	v_mfma_f32_16x16x32_bf16 v[60:63], v[162:165], v[158:161], v[4:7]
	s_lshl_b32 s0, s26, 8
	s_mov_b64 s[2:3], -1
	s_and_b64 vcc, exec, s[24:25]
	v_mfma_f32_16x16x32_bf16 v[56:59], v[166:169], v[158:161], v[0:3]
	v_mfma_f32_16x16x32_bf16 v[52:55], v[170:173], v[158:161], v[40:43]
	v_mfma_f32_16x16x32_bf16 v[48:51], v[174:177], v[158:161], v[48:51]
	v_mfma_f32_16x16x32_bf16 v[44:47], v[162:165], v[216:219], v[178:181]
	v_mfma_f32_16x16x32_bf16 v[40:43], v[166:169], v[216:219], v[232:235]
	v_mfma_f32_16x16x32_bf16 v[36:39], v[170:173], v[216:219], v[236:239]
	v_mfma_f32_16x16x32_bf16 v[32:35], v[174:177], v[216:219], v[182:185]
	v_mfma_f32_16x16x32_bf16 v[28:31], v[162:165], v[146:149], v[240:243]
	v_mfma_f32_16x16x32_bf16 v[24:27], v[166:169], v[146:149], v[244:247]
	v_mfma_f32_16x16x32_bf16 v[20:23], v[170:173], v[146:149], v[248:251]
	v_mfma_f32_16x16x32_bf16 v[16:19], v[174:177], v[146:149], v[186:189]
	v_mfma_f32_16x16x32_bf16 v[12:15], v[162:165], v[206:209], v[128:131]
	v_mfma_f32_16x16x32_bf16 v[8:11], v[166:169], v[206:209], v[136:139]
	v_mfma_f32_16x16x32_bf16 v[4:7], v[170:173], v[206:209], v[140:143]
	v_mfma_f32_16x16x32_bf16 v[0:3], v[174:177], v[206:209], v[154:157]
	s_cbranch_vccz .LBB0_675
	s_mov_b32 s98, 0xbfb8aa3b
	v_mov_b32_e32 v128, v190
	s_lshl_b32 s2, s22, 7
	v_ashrrev_i32_e32 v130, 1, v128
	v_and_b32_e32 v129, 15, v128
	v_and_b32_e32 v130, 0xffffff80, v130
	v_or_b32_e32 v131, s0, v129
	v_or_b32_e32 v129, v130, v129
	v_add_u32_e32 v131, v131, v130
	v_lshl_add_u32 v130, v129, 2, v205
	ds_read_b32 v136, v130
	s_ashr_i32 s3, s2, 31
	s_lshl_b64 s[2:3], s[2:3], 1
	s_add_u32 s2, s66, s2
	s_addc_u32 s3, s67, s3
	s_waitcnt lgkmcnt(0)
	v_lshrrev_b32_e32 v132, 1, v128
	v_and_b32_e32 v144, 0xc0, v128
	v_lshl_add_u64 v[128:129], s[2:3], 0, v[144:145]
	v_and_b32_e32 v144, 24, v132
	v_lshl_add_u64 v[128:129], v[128:129], 0, v[144:145]
	v_and_b32_e32 v144, 8, v144
	v_mul_u32_u24_e32 v144, 3, v144
	v_lshl_add_u64 v[128:129], v[128:129], 0, v[144:145]
	v_mad_i64_i32 v[132:133], s[2:3], v131, s33, v[128:129]
	s_nop 0
	v_pk_mul_f32 v[216:217], v[124:125], v[136:137] op_sel_hi:[1,0]
	v_pk_mul_f32 v[218:219], v[126:127], v[136:137] op_sel_hi:[1,0]
	v_pk_mul_f32 v[220:221], v[216:217], s[98:99] op_sel_hi:[1,0]
	v_pk_mul_f32 v[222:223], v[218:219], s[98:99] op_sel_hi:[1,0]
	v_exp_f32_e32 v220, v220
	v_exp_f32_e32 v221, v221
	v_exp_f32_e32 v222, v222
	v_exp_f32_e32 v223, v223
	v_pk_add_f32 v[220:221], v[220:221], 1.0 op_sel_hi:[1,0]
	v_pk_add_f32 v[222:223], v[222:223], 1.0 op_sel_hi:[1,0]
	v_rcp_f32_e32 v220, v220
	v_rcp_f32_e32 v221, v221
	v_rcp_f32_e32 v222, v222
	v_rcp_f32_e32 v223, v223
	v_pk_mul_f32 v[216:217], v[216:217], v[220:221]
	v_pk_mul_f32 v[218:219], v[218:219], v[222:223]
	v_pk_mul_f32 v[220:221], v[120:121], v[136:137] op_sel_hi:[1,0]
	v_pk_mul_f32 v[222:223], v[122:123], v[136:137] op_sel_hi:[1,0]
	v_pk_mul_f32 v[216:217], v[220:221], v[216:217]
	v_pk_mul_f32 v[218:219], v[222:223], v[218:219]
	v_cvt_pk_bf16_f32 v134, v216, v217
	v_cvt_pk_bf16_f32 v135, v218, v219
	v_mov_b32_e32 v248, v134
	v_mov_b32_e32 v249, v135
	v_mul_f32_e32 v134, v116, v136
	v_mul_f32_e32 v135, 0xbfb8aa3b, v134
	v_exp_f32_e32 v135, v135
	s_nop 0
	v_add_f32_e32 v135, 1.0, v135
	v_rcp_f32_e32 v135, v135
	s_nop 0
	v_mul_f32_e32 v134, v134, v135
	v_mul_f32_e32 v135, v112, v136
	v_mul_f32_e32 v134, v135, v134
	v_mul_f32_e32 v135, v117, v136
	v_mul_f32_e32 v137, 0xbfb8aa3b, v135
	v_exp_f32_e32 v137, v137
	s_nop 0
	v_add_f32_e32 v137, 1.0, v137
	v_rcp_f32_e32 v137, v137
	s_nop 0
	v_mul_f32_e32 v135, v135, v137
	v_mul_f32_e32 v137, v113, v136
	v_mul_f32_e32 v135, v137, v135
	v_mul_f32_e32 v137, v118, v136
	v_mul_f32_e32 v138, 0xbfb8aa3b, v137
	v_exp_f32_e32 v138, v138
	v_cvt_pk_bf16_f32 v134, v134, v135
	s_nop 0
	v_add_f32_e32 v138, 1.0, v138
	v_rcp_f32_e32 v138, v138
	s_nop 0
	v_mul_f32_e32 v137, v137, v138
	v_mul_f32_e32 v138, v114, v136
	v_mul_f32_e32 v137, v138, v137
	v_mul_f32_e32 v138, v119, v136
	v_mul_f32_e32 v139, 0xbfb8aa3b, v138
	v_exp_f32_e32 v139, v139
	v_mul_f32_e32 v136, v115, v136
	v_add_f32_e32 v139, 1.0, v139
	v_rcp_f32_e32 v139, v139
	s_nop 0
	v_mul_f32_e32 v138, v138, v139
	v_mul_f32_e32 v136, v136, v138
	v_cvt_pk_bf16_f32 v135, v137, v136
	v_mov_b32_e32 v250, v134
	v_mov_b32_e32 v251, v135
	s_nop 1
	v_permlane16_swap_b32 v248, v250
	v_permlane16_swap_b32 v249, v251
	flat_store_dwordx4 v[132:133], v[248:251]
	ds_read_b32 v136, v130 offset:64
	v_or_b32_e32 v132, 16, v131
	v_mad_i64_i32 v[132:133], s[2:3], v132, s33, v[128:129]
	s_waitcnt lgkmcnt(0)
	s_nop 0
	v_pk_mul_f32 v[216:217], v[108:109], v[136:137] op_sel_hi:[1,0]
	v_pk_mul_f32 v[218:219], v[110:111], v[136:137] op_sel_hi:[1,0]
	v_pk_mul_f32 v[220:221], v[216:217], s[98:99] op_sel_hi:[1,0]
	v_pk_mul_f32 v[222:223], v[218:219], s[98:99] op_sel_hi:[1,0]
	v_exp_f32_e32 v220, v220
	v_exp_f32_e32 v221, v221
	v_exp_f32_e32 v222, v222
	v_exp_f32_e32 v223, v223
	v_pk_add_f32 v[220:221], v[220:221], 1.0 op_sel_hi:[1,0]
	v_pk_add_f32 v[222:223], v[222:223], 1.0 op_sel_hi:[1,0]
	v_rcp_f32_e32 v220, v220
	v_rcp_f32_e32 v221, v221
	v_rcp_f32_e32 v222, v222
	v_rcp_f32_e32 v223, v223
	v_pk_mul_f32 v[216:217], v[216:217], v[220:221]
	v_pk_mul_f32 v[218:219], v[218:219], v[222:223]
	v_pk_mul_f32 v[220:221], v[104:105], v[136:137] op_sel_hi:[1,0]
	v_pk_mul_f32 v[222:223], v[106:107], v[136:137] op_sel_hi:[1,0]
	v_pk_mul_f32 v[216:217], v[220:221], v[216:217]
	v_pk_mul_f32 v[218:219], v[222:223], v[218:219]
	v_cvt_pk_bf16_f32 v134, v216, v217
	v_cvt_pk_bf16_f32 v135, v218, v219
	v_mov_b32_e32 v248, v134
	v_mov_b32_e32 v249, v135
	v_mul_f32_e32 v134, v100, v136
	v_mul_f32_e32 v135, 0xbfb8aa3b, v134
	v_exp_f32_e32 v135, v135
	s_nop 0
	v_add_f32_e32 v135, 1.0, v135
	v_rcp_f32_e32 v135, v135
	s_nop 0
	v_mul_f32_e32 v134, v134, v135
	v_mul_f32_e32 v135, v96, v136
	v_mul_f32_e32 v134, v135, v134
	v_mul_f32_e32 v135, v101, v136
	v_mul_f32_e32 v137, 0xbfb8aa3b, v135
	v_exp_f32_e32 v137, v137
	s_nop 0
	v_add_f32_e32 v137, 1.0, v137
	v_rcp_f32_e32 v137, v137
	s_nop 0
	v_mul_f32_e32 v135, v135, v137
	v_mul_f32_e32 v137, v97, v136
	v_mul_f32_e32 v135, v137, v135
	v_mul_f32_e32 v137, v102, v136
	v_mul_f32_e32 v138, 0xbfb8aa3b, v137
	v_exp_f32_e32 v138, v138
	v_cvt_pk_bf16_f32 v134, v134, v135
	s_nop 0
	v_add_f32_e32 v138, 1.0, v138
	v_rcp_f32_e32 v138, v138
	s_nop 0
	v_mul_f32_e32 v137, v137, v138
	v_mul_f32_e32 v138, v98, v136
	v_mul_f32_e32 v137, v138, v137
	v_mul_f32_e32 v138, v103, v136
	v_mul_f32_e32 v139, 0xbfb8aa3b, v138
	v_exp_f32_e32 v139, v139
	v_mul_f32_e32 v136, v99, v136
	v_add_f32_e32 v139, 1.0, v139
	v_rcp_f32_e32 v139, v139
	s_nop 0
	v_mul_f32_e32 v138, v138, v139
	v_mul_f32_e32 v136, v136, v138
	v_cvt_pk_bf16_f32 v135, v137, v136
	v_mov_b32_e32 v250, v134
	v_mov_b32_e32 v251, v135
	s_nop 1
	v_permlane16_swap_b32 v248, v250
	v_permlane16_swap_b32 v249, v251
	flat_store_dwordx4 v[132:133], v[248:251]
	ds_read_b32 v136, v130 offset:128
	v_or_b32_e32 v132, 32, v131
	v_mad_i64_i32 v[132:133], s[2:3], v132, s33, v[128:129]
	s_waitcnt lgkmcnt(0)
	s_nop 0
	v_pk_mul_f32 v[216:217], v[92:93], v[136:137] op_sel_hi:[1,0]
	v_pk_mul_f32 v[218:219], v[94:95], v[136:137] op_sel_hi:[1,0]
	v_pk_mul_f32 v[220:221], v[216:217], s[98:99] op_sel_hi:[1,0]
	v_pk_mul_f32 v[222:223], v[218:219], s[98:99] op_sel_hi:[1,0]
	v_exp_f32_e32 v220, v220
	v_exp_f32_e32 v221, v221
	v_exp_f32_e32 v222, v222
	v_exp_f32_e32 v223, v223
	v_pk_add_f32 v[220:221], v[220:221], 1.0 op_sel_hi:[1,0]
	v_pk_add_f32 v[222:223], v[222:223], 1.0 op_sel_hi:[1,0]
	v_rcp_f32_e32 v220, v220
	v_rcp_f32_e32 v221, v221
	v_rcp_f32_e32 v222, v222
	v_rcp_f32_e32 v223, v223
	v_pk_mul_f32 v[216:217], v[216:217], v[220:221]
	v_pk_mul_f32 v[218:219], v[218:219], v[222:223]
	v_pk_mul_f32 v[220:221], v[88:89], v[136:137] op_sel_hi:[1,0]
	v_pk_mul_f32 v[222:223], v[90:91], v[136:137] op_sel_hi:[1,0]
	v_pk_mul_f32 v[216:217], v[220:221], v[216:217]
	v_pk_mul_f32 v[218:219], v[222:223], v[218:219]
	v_cvt_pk_bf16_f32 v134, v216, v217
	v_cvt_pk_bf16_f32 v135, v218, v219
	v_mov_b32_e32 v248, v134
	v_mov_b32_e32 v249, v135
	v_mul_f32_e32 v134, v84, v136
	v_mul_f32_e32 v135, 0xbfb8aa3b, v134
	v_exp_f32_e32 v135, v135
	s_nop 0
	v_add_f32_e32 v135, 1.0, v135
	v_rcp_f32_e32 v135, v135
	s_nop 0
	v_mul_f32_e32 v134, v134, v135
	v_mul_f32_e32 v135, v80, v136
	v_mul_f32_e32 v134, v135, v134
	v_mul_f32_e32 v135, v85, v136
	v_mul_f32_e32 v137, 0xbfb8aa3b, v135
	v_exp_f32_e32 v137, v137
	s_nop 0
	v_add_f32_e32 v137, 1.0, v137
	v_rcp_f32_e32 v137, v137
	s_nop 0
	v_mul_f32_e32 v135, v135, v137
	v_mul_f32_e32 v137, v81, v136
	v_mul_f32_e32 v135, v137, v135
	v_mul_f32_e32 v137, v86, v136
	v_mul_f32_e32 v138, 0xbfb8aa3b, v137
	v_exp_f32_e32 v138, v138
	v_cvt_pk_bf16_f32 v134, v134, v135
	s_nop 0
	v_add_f32_e32 v138, 1.0, v138
	v_rcp_f32_e32 v138, v138
	s_nop 0
	v_mul_f32_e32 v137, v137, v138
	v_mul_f32_e32 v138, v82, v136
	v_mul_f32_e32 v137, v138, v137
	v_mul_f32_e32 v138, v87, v136
	v_mul_f32_e32 v139, 0xbfb8aa3b, v138
	v_exp_f32_e32 v139, v139
	v_mul_f32_e32 v136, v83, v136
	v_add_f32_e32 v139, 1.0, v139
	v_rcp_f32_e32 v139, v139
	s_nop 0
	v_mul_f32_e32 v138, v138, v139
	v_mul_f32_e32 v136, v136, v138
	v_cvt_pk_bf16_f32 v135, v137, v136
	v_mov_b32_e32 v250, v134
	v_mov_b32_e32 v251, v135
	s_nop 1
	v_permlane16_swap_b32 v248, v250
	v_permlane16_swap_b32 v249, v251
	flat_store_dwordx4 v[132:133], v[248:251]
	ds_read_b32 v136, v130 offset:192
	v_or_b32_e32 v132, 48, v131
	v_mad_i64_i32 v[132:133], s[2:3], v132, s33, v[128:129]
	s_waitcnt lgkmcnt(0)
	s_nop 0
	v_pk_mul_f32 v[216:217], v[76:77], v[136:137] op_sel_hi:[1,0]
	v_pk_mul_f32 v[218:219], v[78:79], v[136:137] op_sel_hi:[1,0]
	v_pk_mul_f32 v[220:221], v[216:217], s[98:99] op_sel_hi:[1,0]
	v_pk_mul_f32 v[222:223], v[218:219], s[98:99] op_sel_hi:[1,0]
	v_exp_f32_e32 v220, v220
	v_exp_f32_e32 v221, v221
	v_exp_f32_e32 v222, v222
	v_exp_f32_e32 v223, v223
	v_pk_add_f32 v[220:221], v[220:221], 1.0 op_sel_hi:[1,0]
	v_pk_add_f32 v[222:223], v[222:223], 1.0 op_sel_hi:[1,0]
	v_rcp_f32_e32 v220, v220
	v_rcp_f32_e32 v221, v221
	v_rcp_f32_e32 v222, v222
	v_rcp_f32_e32 v223, v223
	v_pk_mul_f32 v[216:217], v[216:217], v[220:221]
	v_pk_mul_f32 v[218:219], v[218:219], v[222:223]
	v_pk_mul_f32 v[220:221], v[72:73], v[136:137] op_sel_hi:[1,0]
	v_pk_mul_f32 v[222:223], v[74:75], v[136:137] op_sel_hi:[1,0]
	v_pk_mul_f32 v[216:217], v[220:221], v[216:217]
	v_pk_mul_f32 v[218:219], v[222:223], v[218:219]
	v_cvt_pk_bf16_f32 v134, v216, v217
	v_cvt_pk_bf16_f32 v135, v218, v219
	v_mov_b32_e32 v248, v134
	v_mov_b32_e32 v249, v135
	v_mul_f32_e32 v134, v68, v136
	v_mul_f32_e32 v135, 0xbfb8aa3b, v134
	v_exp_f32_e32 v135, v135
	s_nop 0
	v_add_f32_e32 v135, 1.0, v135
	v_rcp_f32_e32 v135, v135
	s_nop 0
	v_mul_f32_e32 v134, v134, v135
	v_mul_f32_e32 v135, v64, v136
	v_mul_f32_e32 v134, v135, v134
	v_mul_f32_e32 v135, v69, v136
	v_mul_f32_e32 v137, 0xbfb8aa3b, v135
	v_exp_f32_e32 v137, v137
	s_nop 0
	v_add_f32_e32 v137, 1.0, v137
	v_rcp_f32_e32 v137, v137
	s_nop 0
	v_mul_f32_e32 v135, v135, v137
	v_mul_f32_e32 v137, v65, v136
	v_mul_f32_e32 v135, v137, v135
	v_mul_f32_e32 v137, v70, v136
	v_mul_f32_e32 v138, 0xbfb8aa3b, v137
	v_exp_f32_e32 v138, v138
	v_cvt_pk_bf16_f32 v134, v134, v135
	s_nop 0
	v_add_f32_e32 v138, 1.0, v138
	v_rcp_f32_e32 v138, v138
	s_nop 0
	v_mul_f32_e32 v137, v137, v138
	v_mul_f32_e32 v138, v66, v136
	v_mul_f32_e32 v137, v138, v137
	v_mul_f32_e32 v138, v71, v136
	v_mul_f32_e32 v139, 0xbfb8aa3b, v138
	v_exp_f32_e32 v139, v139
	v_mul_f32_e32 v136, v67, v136
	v_add_f32_e32 v139, 1.0, v139
	v_rcp_f32_e32 v139, v139
	s_nop 0
	v_mul_f32_e32 v138, v138, v139
	v_mul_f32_e32 v136, v136, v138
	v_cvt_pk_bf16_f32 v135, v137, v136
	v_mov_b32_e32 v250, v134
	v_mov_b32_e32 v251, v135
	s_nop 1
	v_permlane16_swap_b32 v248, v250
	v_permlane16_swap_b32 v249, v251
	flat_store_dwordx4 v[132:133], v[248:251]
	ds_read_b32 v136, v130 offset:256
	v_or_b32_e32 v132, 64, v131
	v_mad_i64_i32 v[132:133], s[2:3], v132, s33, v[128:129]
	s_waitcnt lgkmcnt(0)
	s_nop 0
	v_pk_mul_f32 v[216:217], v[60:61], v[136:137] op_sel_hi:[1,0]
	v_pk_mul_f32 v[218:219], v[62:63], v[136:137] op_sel_hi:[1,0]
	v_pk_mul_f32 v[220:221], v[216:217], s[98:99] op_sel_hi:[1,0]
	v_pk_mul_f32 v[222:223], v[218:219], s[98:99] op_sel_hi:[1,0]
	v_exp_f32_e32 v220, v220
	v_exp_f32_e32 v221, v221
	v_exp_f32_e32 v222, v222
	v_exp_f32_e32 v223, v223
	v_pk_add_f32 v[220:221], v[220:221], 1.0 op_sel_hi:[1,0]
	v_pk_add_f32 v[222:223], v[222:223], 1.0 op_sel_hi:[1,0]
	v_rcp_f32_e32 v220, v220
	v_rcp_f32_e32 v221, v221
	v_rcp_f32_e32 v222, v222
	v_rcp_f32_e32 v223, v223
	v_pk_mul_f32 v[216:217], v[216:217], v[220:221]
	v_pk_mul_f32 v[218:219], v[218:219], v[222:223]
	v_pk_mul_f32 v[220:221], v[56:57], v[136:137] op_sel_hi:[1,0]
	v_pk_mul_f32 v[222:223], v[58:59], v[136:137] op_sel_hi:[1,0]
	v_pk_mul_f32 v[216:217], v[220:221], v[216:217]
	v_pk_mul_f32 v[218:219], v[222:223], v[218:219]
	v_cvt_pk_bf16_f32 v134, v216, v217
	v_cvt_pk_bf16_f32 v135, v218, v219
	v_mov_b32_e32 v248, v134
	v_mov_b32_e32 v249, v135
	v_mul_f32_e32 v134, v52, v136
	v_mul_f32_e32 v135, 0xbfb8aa3b, v134
	v_exp_f32_e32 v135, v135
	s_nop 0
	v_add_f32_e32 v135, 1.0, v135
	v_rcp_f32_e32 v135, v135
	s_nop 0
	v_mul_f32_e32 v134, v134, v135
	v_mul_f32_e32 v135, v48, v136
	v_mul_f32_e32 v134, v135, v134
	v_mul_f32_e32 v135, v53, v136
	v_mul_f32_e32 v137, 0xbfb8aa3b, v135
	v_exp_f32_e32 v137, v137
	s_nop 0
	v_add_f32_e32 v137, 1.0, v137
	v_rcp_f32_e32 v137, v137
	s_nop 0
	v_mul_f32_e32 v135, v135, v137
	v_mul_f32_e32 v137, v49, v136
	v_mul_f32_e32 v135, v137, v135
	v_mul_f32_e32 v137, v54, v136
	v_mul_f32_e32 v138, 0xbfb8aa3b, v137
	v_exp_f32_e32 v138, v138
	v_cvt_pk_bf16_f32 v134, v134, v135
	s_nop 0
	v_add_f32_e32 v138, 1.0, v138
	v_rcp_f32_e32 v138, v138
	s_nop 0
	v_mul_f32_e32 v137, v137, v138
	v_mul_f32_e32 v138, v50, v136
	v_mul_f32_e32 v137, v138, v137
	v_mul_f32_e32 v138, v55, v136
	v_mul_f32_e32 v139, 0xbfb8aa3b, v138
	v_exp_f32_e32 v139, v139
	v_mul_f32_e32 v136, v51, v136
	v_add_f32_e32 v139, 1.0, v139
	v_rcp_f32_e32 v139, v139
	s_nop 0
	v_mul_f32_e32 v138, v138, v139
	v_mul_f32_e32 v136, v136, v138
	v_cvt_pk_bf16_f32 v135, v137, v136
	v_mov_b32_e32 v250, v134
	v_mov_b32_e32 v251, v135
	s_nop 1
	v_permlane16_swap_b32 v248, v250
	v_permlane16_swap_b32 v249, v251
	flat_store_dwordx4 v[132:133], v[248:251]
	ds_read_b32 v136, v130 offset:320
	v_or_b32_e32 v132, 0x50, v131
	v_mad_i64_i32 v[132:133], s[2:3], v132, s33, v[128:129]
	s_waitcnt lgkmcnt(0)
	s_nop 0
	v_pk_mul_f32 v[216:217], v[44:45], v[136:137] op_sel_hi:[1,0]
	v_pk_mul_f32 v[218:219], v[46:47], v[136:137] op_sel_hi:[1,0]
	v_pk_mul_f32 v[220:221], v[216:217], s[98:99] op_sel_hi:[1,0]
	v_pk_mul_f32 v[222:223], v[218:219], s[98:99] op_sel_hi:[1,0]
	v_exp_f32_e32 v220, v220
	v_exp_f32_e32 v221, v221
	v_exp_f32_e32 v222, v222
	v_exp_f32_e32 v223, v223
	v_pk_add_f32 v[220:221], v[220:221], 1.0 op_sel_hi:[1,0]
	v_pk_add_f32 v[222:223], v[222:223], 1.0 op_sel_hi:[1,0]
	v_rcp_f32_e32 v220, v220
	v_rcp_f32_e32 v221, v221
	v_rcp_f32_e32 v222, v222
	v_rcp_f32_e32 v223, v223
	v_pk_mul_f32 v[216:217], v[216:217], v[220:221]
	v_pk_mul_f32 v[218:219], v[218:219], v[222:223]
	v_pk_mul_f32 v[220:221], v[40:41], v[136:137] op_sel_hi:[1,0]
	v_pk_mul_f32 v[222:223], v[42:43], v[136:137] op_sel_hi:[1,0]
	v_pk_mul_f32 v[216:217], v[220:221], v[216:217]
	v_pk_mul_f32 v[218:219], v[222:223], v[218:219]
	v_cvt_pk_bf16_f32 v134, v216, v217
	v_cvt_pk_bf16_f32 v135, v218, v219
	v_mov_b32_e32 v248, v134
	v_mov_b32_e32 v249, v135
	v_mul_f32_e32 v134, v36, v136
	v_mul_f32_e32 v135, 0xbfb8aa3b, v134
	v_exp_f32_e32 v135, v135
	s_nop 0
	v_add_f32_e32 v135, 1.0, v135
	v_rcp_f32_e32 v135, v135
	s_nop 0
	v_mul_f32_e32 v134, v134, v135
	v_mul_f32_e32 v135, v32, v136
	v_mul_f32_e32 v134, v135, v134
	v_mul_f32_e32 v135, v37, v136
	v_mul_f32_e32 v137, 0xbfb8aa3b, v135
	v_exp_f32_e32 v137, v137
	s_nop 0
	v_add_f32_e32 v137, 1.0, v137
	v_rcp_f32_e32 v137, v137
	s_nop 0
	v_mul_f32_e32 v135, v135, v137
	v_mul_f32_e32 v137, v33, v136
	v_mul_f32_e32 v135, v137, v135
	v_mul_f32_e32 v137, v38, v136
	v_mul_f32_e32 v138, 0xbfb8aa3b, v137
	v_exp_f32_e32 v138, v138
	v_cvt_pk_bf16_f32 v134, v134, v135
	s_nop 0
	v_add_f32_e32 v138, 1.0, v138
	v_rcp_f32_e32 v138, v138
	s_nop 0
	v_mul_f32_e32 v137, v137, v138
	v_mul_f32_e32 v138, v34, v136
	v_mul_f32_e32 v137, v138, v137
	v_mul_f32_e32 v138, v39, v136
	v_mul_f32_e32 v139, 0xbfb8aa3b, v138
	v_exp_f32_e32 v139, v139
	v_mul_f32_e32 v136, v35, v136
	v_add_f32_e32 v139, 1.0, v139
	v_rcp_f32_e32 v139, v139
	s_nop 0
	v_mul_f32_e32 v138, v138, v139
	v_mul_f32_e32 v136, v136, v138
	v_cvt_pk_bf16_f32 v135, v137, v136
	v_mov_b32_e32 v250, v134
	v_mov_b32_e32 v251, v135
	s_nop 1
	v_permlane16_swap_b32 v248, v250
	v_permlane16_swap_b32 v249, v251
	flat_store_dwordx4 v[132:133], v[248:251]
	ds_read_b32 v136, v130 offset:384
	v_or_b32_e32 v132, 0x60, v131
	v_mad_i64_i32 v[132:133], s[2:3], v132, s33, v[128:129]
	v_or_b32_e32 v131, 0x70, v131
	s_waitcnt lgkmcnt(0)
	v_mad_i64_i32 v[128:129], s[2:3], v131, s33, v[128:129]
	s_nop 0
	v_pk_mul_f32 v[216:217], v[28:29], v[136:137] op_sel_hi:[1,0]
	v_pk_mul_f32 v[218:219], v[30:31], v[136:137] op_sel_hi:[1,0]
	v_pk_mul_f32 v[220:221], v[216:217], s[98:99] op_sel_hi:[1,0]
	v_pk_mul_f32 v[222:223], v[218:219], s[98:99] op_sel_hi:[1,0]
	v_exp_f32_e32 v220, v220
	v_exp_f32_e32 v221, v221
	v_exp_f32_e32 v222, v222
	v_exp_f32_e32 v223, v223
	v_pk_add_f32 v[220:221], v[220:221], 1.0 op_sel_hi:[1,0]
	v_pk_add_f32 v[222:223], v[222:223], 1.0 op_sel_hi:[1,0]
	v_rcp_f32_e32 v220, v220
	v_rcp_f32_e32 v221, v221
	v_rcp_f32_e32 v222, v222
	v_rcp_f32_e32 v223, v223
	v_pk_mul_f32 v[216:217], v[216:217], v[220:221]
	v_pk_mul_f32 v[218:219], v[218:219], v[222:223]
	v_pk_mul_f32 v[220:221], v[24:25], v[136:137] op_sel_hi:[1,0]
	v_pk_mul_f32 v[222:223], v[26:27], v[136:137] op_sel_hi:[1,0]
	v_pk_mul_f32 v[216:217], v[220:221], v[216:217]
	v_pk_mul_f32 v[218:219], v[222:223], v[218:219]
	v_cvt_pk_bf16_f32 v134, v216, v217
	v_cvt_pk_bf16_f32 v135, v218, v219
	v_mov_b32_e32 v248, v134
	v_mov_b32_e32 v249, v135
	v_mul_f32_e32 v134, v20, v136
	v_mul_f32_e32 v135, 0xbfb8aa3b, v134
	v_exp_f32_e32 v135, v135
	s_nop 0
	v_add_f32_e32 v135, 1.0, v135
	v_rcp_f32_e32 v135, v135
	s_nop 0
	v_mul_f32_e32 v134, v134, v135
	v_mul_f32_e32 v135, v16, v136
	v_mul_f32_e32 v134, v135, v134
	v_mul_f32_e32 v135, v21, v136
	v_mul_f32_e32 v137, 0xbfb8aa3b, v135
	v_exp_f32_e32 v137, v137
	s_nop 0
	v_add_f32_e32 v137, 1.0, v137
	v_rcp_f32_e32 v137, v137
	s_nop 0
	v_mul_f32_e32 v135, v135, v137
	v_mul_f32_e32 v137, v17, v136
	v_mul_f32_e32 v135, v137, v135
	v_mul_f32_e32 v137, v22, v136
	v_mul_f32_e32 v138, 0xbfb8aa3b, v137
	v_exp_f32_e32 v138, v138
	v_cvt_pk_bf16_f32 v134, v134, v135
	s_nop 0
	v_add_f32_e32 v138, 1.0, v138
	v_rcp_f32_e32 v138, v138
	s_nop 0
	v_mul_f32_e32 v137, v137, v138
	v_mul_f32_e32 v138, v18, v136
	v_mul_f32_e32 v137, v138, v137
	v_mul_f32_e32 v138, v23, v136
	v_mul_f32_e32 v139, 0xbfb8aa3b, v138
	v_exp_f32_e32 v139, v139
	v_mul_f32_e32 v136, v19, v136
	v_add_f32_e32 v139, 1.0, v139
	v_rcp_f32_e32 v139, v139
	s_nop 0
	v_mul_f32_e32 v138, v138, v139
	v_mul_f32_e32 v136, v136, v138
	v_cvt_pk_bf16_f32 v135, v137, v136
	v_mov_b32_e32 v250, v134
	v_mov_b32_e32 v251, v135
	s_nop 1
	v_permlane16_swap_b32 v248, v250
	v_permlane16_swap_b32 v249, v251
	flat_store_dwordx4 v[132:133], v[248:251]
	ds_read_b32 v132, v130 offset:448
	s_waitcnt lgkmcnt(0)
	s_nop 0
	v_pk_mul_f32 v[216:217], v[12:13], v[132:133] op_sel_hi:[1,0]
	v_pk_mul_f32 v[218:219], v[14:15], v[132:133] op_sel_hi:[1,0]
	v_pk_mul_f32 v[220:221], v[216:217], s[98:99] op_sel_hi:[1,0]
	v_pk_mul_f32 v[222:223], v[218:219], s[98:99] op_sel_hi:[1,0]
	v_exp_f32_e32 v220, v220
	v_exp_f32_e32 v221, v221
	v_exp_f32_e32 v222, v222
	v_exp_f32_e32 v223, v223
	v_pk_add_f32 v[220:221], v[220:221], 1.0 op_sel_hi:[1,0]
	v_pk_add_f32 v[222:223], v[222:223], 1.0 op_sel_hi:[1,0]
	v_rcp_f32_e32 v220, v220
	v_rcp_f32_e32 v221, v221
	v_rcp_f32_e32 v222, v222
	v_rcp_f32_e32 v223, v223
	v_pk_mul_f32 v[216:217], v[216:217], v[220:221]
	v_pk_mul_f32 v[218:219], v[218:219], v[222:223]
	v_pk_mul_f32 v[220:221], v[8:9], v[132:133] op_sel_hi:[1,0]
	v_pk_mul_f32 v[222:223], v[10:11], v[132:133] op_sel_hi:[1,0]
	v_pk_mul_f32 v[216:217], v[220:221], v[216:217]
	v_pk_mul_f32 v[218:219], v[222:223], v[218:219]
	v_cvt_pk_bf16_f32 v130, v216, v217
	v_cvt_pk_bf16_f32 v131, v218, v219
	v_mov_b32_e32 v248, v130
	v_mov_b32_e32 v249, v131
	v_mul_f32_e32 v130, v4, v132
	v_mul_f32_e32 v131, 0xbfb8aa3b, v130
	v_exp_f32_e32 v131, v131
	s_nop 0
	v_add_f32_e32 v131, 1.0, v131
	v_rcp_f32_e32 v131, v131
	s_nop 0
	v_mul_f32_e32 v130, v130, v131
	v_mul_f32_e32 v131, v0, v132
	v_mul_f32_e32 v130, v131, v130
	v_mul_f32_e32 v131, v5, v132
	v_mul_f32_e32 v133, 0xbfb8aa3b, v131
	v_exp_f32_e32 v133, v133
	s_nop 0
	v_add_f32_e32 v133, 1.0, v133
	v_rcp_f32_e32 v133, v133
	s_nop 0
	v_mul_f32_e32 v131, v131, v133
	v_mul_f32_e32 v133, v1, v132
	v_mul_f32_e32 v131, v133, v131
	v_mul_f32_e32 v133, v6, v132
	v_mul_f32_e32 v134, 0xbfb8aa3b, v133
	v_exp_f32_e32 v134, v134
	v_cvt_pk_bf16_f32 v130, v130, v131
	s_nop 0
	v_add_f32_e32 v134, 1.0, v134
	v_rcp_f32_e32 v134, v134
	s_nop 0
	v_mul_f32_e32 v133, v133, v134
	v_mul_f32_e32 v134, v2, v132
	v_mul_f32_e32 v133, v134, v133
	v_mul_f32_e32 v134, v7, v132
	v_mul_f32_e32 v135, 0xbfb8aa3b, v134
	v_exp_f32_e32 v135, v135
	v_mul_f32_e32 v132, v3, v132
	v_add_f32_e32 v135, 1.0, v135
	v_rcp_f32_e32 v135, v135
	s_nop 0
	v_mul_f32_e32 v134, v134, v135
	v_mul_f32_e32 v132, v132, v134
	v_cvt_pk_bf16_f32 v131, v133, v132
	v_mov_b32_e32 v250, v130
	v_mov_b32_e32 v251, v131
	s_nop 1
	v_permlane16_swap_b32 v248, v250
	v_permlane16_swap_b32 v249, v251
	flat_store_dwordx4 v[128:129], v[248:251]
	s_cbranch_execnz .LBB0_653
	s_branch .LBB0_676
